# normmod2 -> FFN-up barrier replaced by H-panel counters plus an all-X-panels condition (ACT/edge stores alias MERGED/YS/Z); H rows written through
# baseline (speedup 1.0000x reference)
.LBB0_8:
	v_writelane_b32 v254, s78, 24
	s_mov_b32 s0, s49
	s_ashr_i32 s1, s0, 31
	v_writelane_b32 v254, s79, 25
	v_writelane_b32 v254, s76, 26
	v_readlane_b32 s2, v253, 3
	v_readlane_b32 s3, v253, 4
	v_writelane_b32 v254, s77, 27
	v_writelane_b32 v254, s74, 28
	s_add_u32 s0, s2, s0
	s_addc_u32 s1, s3, s1
	v_writelane_b32 v254, s75, 29
	v_writelane_b32 v254, s66, 30
	v_readlane_b32 s24, v253, 62
	v_writelane_b32 v254, s67, 31
	v_readlane_b32 s25, v253, 63
	s_load_dwordx16 s[52:67], s[0:1], 0x0
	s_load_dwordx2 s[30:31], s[0:1], 0x70
	s_load_dwordx4 s[36:39], s[0:1], 0x60
	s_load_dwordx8 s[12:19], s[0:1], 0x40
	s_load_dwordx2 s[2:3], s[0:1], 0x88
	s_load_dwordx8 s[68:75], s[0:1], 0x98
	s_load_dwordx16 s[80:95], s[0:1], 0xc0
	s_load_dwordx4 s[96:99], s[0:1], 0x120
	s_load_dwordx8 s[4:11], s[0:1], 0x100
	s_waitcnt lgkmcnt(0)
	s_movk_i32 s100, 0
	s_cmp_eq_u32 s46, 6
	s_cselect_b32 s100, 8, s100
	s_cmp_eq_u32 s46, 10
	s_cselect_b32 s100, 16, s100
	s_cmp_eq_u32 s46, 15
	s_cselect_b32 s100, 24, s100
	s_cmp_eq_u32 s46, 19
	s_cselect_b32 s100, 32, s100
	s_cmp_eq_u32 s46, 1
	s_cselect_b32 s100, 32, s100
	s_cmp_eq_u32 s46, 7
	s_cselect_b32 s100, 8, s100
	s_cmp_eq_u32 s46, 16
	s_cselect_b32 s100, 24, s100
	s_cmp_eq_u32 s100, 0
	s_cbranch_scc1 .Lpf_done
	v_lshrrev_b32_e32 v2, 6, v1
	s_nop 1
	v_readfirstlane_b32 s0, v2
	s_cmp_lg_u32 s0, 0
	s_cbranch_scc1 .Lpf_wait
	v_readlane_b32 s0, v253, 0
	s_lshr_b32 s1, s0, 4
	s_mov_b32 vcc_lo, 15
	s_mov_b32 vcc_hi, 0
	s_cmp_eq_u32 s46, 19
	s_cbranch_scc0 .Lpf_t1
	s_lshr_b32 s1, s0, 5
	s_mov_b32 vcc_lo, 7

.Lpf_t3:
	s_cmp_eq_u32 s46, 7
	s_cbranch_scc1 .Lpf_te
	s_cmp_eq_u32 s46, 16
	s_cbranch_scc0 .Lpf_t4
.Lpf_te:
	s_mov_b32 s1, 0
	s_mov_b32 vcc_lo, 0
	s_mov_b32 vcc_hi, 0

.Lpf_h:
	s_cmp_eq_u32 s46, 7
	s_cselect_b32 s100, 16, 32
	v_mov_b32_e32 v3, s100
	v_readlane_b32 vcc_lo, v253, 0
	s_and_b32 vcc_hi, vcc_lo, 7
	s_lshl_b32 vcc_hi, vcc_hi, 2
	s_bfe_u32 vcc_lo, vcc_lo, 0x20003
	s_or_b32 vcc_lo, vcc_lo, vcc_hi
	s_lshl_b32 vcc_lo, vcc_lo, 2
	s_add_u32 vcc_lo, vcc_lo, 0x80
	v_mov_b32_e32 v4, vcc_lo
	s_movk_i32 s100, 0x1000

.LBB0_205:
	v_mov_b32_e32 v4, v1
	v_cmp_lt_i32_e32 vcc, v196, v195
	v_and_b32_e32 v2, 63, v4
	v_lshlrev_b32_e32 v162, 3, v2
	v_lshl_add_u64 v[2:3], s[14:15], 0, v[12:13]
	v_lshl_add_u64 v[2:3], v[2:3], 0, v[162:163]
	global_load_dwordx2 v[20:21], v[2:3], off sc1
	global_load_dwordx2 v[40:41], v[2:3], off offset:512 sc1
	global_load_dwordx2 v[24:25], v[2:3], off offset:1024 sc1
	global_load_dwordx2 v[42:43], v[2:3], off offset:1536 sc1
	global_load_dwordx2 v[30:31], v[2:3], off offset:2048 sc1
	global_load_dwordx2 v[38:39], v[2:3], off offset:2560 sc1
	global_load_dwordx2 v[22:23], v[2:3], off offset:3072 sc1
	global_load_dwordx2 v[46:47], v[2:3], off offset:3584 sc1
	v_cndmask_b32_e32 v2, v194, v196, vcc
	v_cmp_lt_i32_e32 vcc, v197, v195
	v_lshlrev_b32_e32 v11, 2, v2
	s_mul_i32 s0, s82, 5
	v_cndmask_b32_e32 v2, v194, v197, vcc
	v_cmp_lt_i32_e32 vcc, v198, v195
	s_waitcnt vmcnt(20)
	v_lshlrev_b32_e32 v74, 2, v2
	v_mov_b32_e32 v15, v163
	v_cndmask_b32_e32 v2, v194, v198, vcc
	v_cmp_lt_i32_e32 vcc, v199, v195
	v_lshlrev_b32_e32 v75, 2, v2
	s_waitcnt vmcnt(7)
	v_and_b32_e32 v33, 0xffff0000, v20
	v_cndmask_b32_e32 v2, v194, v199, vcc
	v_cmp_lt_i32_e32 vcc, v200, v195
	v_lshlrev_b32_e32 v76, 2, v2
	s_waitcnt vmcnt(6)
	v_and_b32_e32 v59, 0xffff0000, v40
	v_cndmask_b32_e32 v2, v194, v200, vcc
	v_cmp_lt_i32_e32 vcc, v201, v195
	v_lshlrev_b32_e32 v77, 2, v2
	v_lshlrev_b32_e32 v32, 16, v20
	v_cndmask_b32_e32 v2, v194, v201, vcc
	v_lshlrev_b32_e32 v78, 2, v2
	v_add_u32_e32 v2, 0xfffff000, v10
	v_lshrrev_b32_e32 v2, 10, v2
	v_add_u32_e32 v2, 1, v2
	v_cmp_lt_i32_e32 vcc, s17, v10
	v_lshlrev_b32_e32 v58, 16, v40
	v_mov_b32_e32 v52, v33
	v_cndmask_b32_e32 v2, 0, v2, vcc
	v_add_u32_e32 v5, s0, v2
	v_mov_b64_e32 v[2:3], s[40:41]
	v_mad_i64_i32 v[2:3], s[0:1], v5, s29, v[2:3]
	s_mov_b64 s[0:1], 0x3000
	s_nop 0
	v_lshl_add_u64 v[44:45], v[2:3], 0, s[0:1]
	v_lshl_add_u64 v[60:61], v[2:3], 0, s[36:37]
	v_lshlrev_b32_e32 v2, 4, v4
	v_and_b32_e32 v14, 0x3f0, v2
	v_lshl_add_u64 v[2:3], v[44:45], 0, v[14:15]
	v_lshl_add_u64 v[16:17], v[60:61], 0, v[14:15]
	global_load_dwordx4 v[2:5], v[2:3], off
	v_mov_b32_e32 v53, v59
	global_load_dwordx4 v[16:19], v[16:17], off
	v_lshlrev_b32_e32 v28, 16, v21
	global_load_dwordx4 v[6:9], v14, s[6:7]
	v_lshlrev_b32_e32 v56, 16, v41
	v_mov_b32_e32 v50, v32
	v_mov_b32_e32 v51, v58
	v_pk_mul_f32 v[52:53], v[52:53], v[52:53]
	v_and_b32_e32 v57, 0xffff0000, v41
	v_mov_b32_e32 v40, v28
	v_mov_b32_e32 v41, v56
	v_pk_fma_f32 v[50:51], v[50:51], v[50:51], v[52:53]
	v_and_b32_e32 v29, 0xffff0000, v21
	s_waitcnt vmcnt(6)
	v_and_b32_e32 v35, 0xffff0000, v30
	v_pk_fma_f32 v[40:41], v[40:41], v[40:41], v[50:51]
	s_waitcnt vmcnt(5)
	v_and_b32_e32 v51, 0xffff0000, v38
	v_lshlrev_b32_e32 v34, 16, v30
	v_mov_b32_e32 v48, v29
	v_mov_b32_e32 v49, v57
	v_lshlrev_b32_e32 v50, 16, v38
	v_mov_b32_e32 v54, v35
	v_mov_b32_e32 v55, v51
	v_lshlrev_b32_e32 v26, 16, v31
	v_pk_fma_f32 v[62:63], v[48:49], v[48:49], v[40:41]
	v_lshlrev_b32_e32 v48, 16, v39
	v_mov_b32_e32 v52, v34
	v_mov_b32_e32 v53, v50
	v_pk_mul_f32 v[54:55], v[54:55], v[54:55]
	v_and_b32_e32 v27, 0xffff0000, v31
	v_and_b32_e32 v49, 0xffff0000, v39
	v_mov_b32_e32 v38, v26
	v_mov_b32_e32 v39, v48
	v_pk_fma_f32 v[52:53], v[52:53], v[52:53], v[54:55]
	v_mov_b32_e32 v40, v27
	v_mov_b32_e32 v41, v49
	v_pk_fma_f32 v[38:39], v[38:39], v[38:39], v[52:53]
	v_and_b32_e32 v67, 0xffff0000, v24
	v_and_b32_e32 v71, 0xffff0000, v42
	v_pk_fma_f32 v[68:69], v[40:41], v[40:41], v[38:39]
	v_lshlrev_b32_e32 v66, 16, v24
	v_lshlrev_b32_e32 v70, 16, v42
	v_mov_b32_e32 v80, v67
	v_mov_b32_e32 v81, v71
	v_lshlrev_b32_e32 v64, 16, v25
	s_waitcnt vmcnt(4)
	v_lshlrev_b32_e32 v52, 16, v23
	v_and_b32_e32 v53, 0xffff0000, v23
	v_lshlrev_b32_e32 v54, 16, v22
	v_and_b32_e32 v55, 0xffff0000, v22
	v_mov_b32_e32 v72, v66
	v_mov_b32_e32 v73, v70
	v_pk_mul_f32 v[80:81], v[80:81], v[80:81]
	v_and_b32_e32 v65, 0xffff0000, v25
	v_mov_b32_e32 v42, v64
	v_pk_fma_f32 v[72:73], v[72:73], v[72:73], v[80:81]
	v_mov_b32_e32 v84, v55
	v_mov_b32_e32 v82, v54
	v_mov_b32_e32 v80, v53
	v_add_u32_e32 v10, s16, v10
	s_waitcnt vmcnt(1)
	v_pk_add_f32 v[20:21], v[16:17], 1.0 op_sel_hi:[1,0]
	v_lshl_add_u64 v[16:17], s[18:19], 0, v[12:13]
	v_lshl_add_u64 v[16:17], v[16:17], 0, v[162:163]
	v_or_b32_e32 v162, 0x400, v14
	v_lshl_add_u64 v[36:37], v[44:45], 0, v[162:163]
	v_lshl_add_u64 v[30:31], v[60:61], 0, v[162:163]
	v_or_b32_e32 v162, 0x800, v14
	v_lshl_add_u64 v[40:41], v[44:45], 0, v[162:163]
	v_lshl_add_u64 v[38:39], v[60:61], 0, v[162:163]
	v_or_b32_e32 v162, 0xc00, v14
	v_lshl_add_u64 v[22:23], v[60:61], 0, v[162:163]
	v_lshlrev_b32_e32 v60, 16, v43
	v_and_b32_e32 v61, 0xffff0000, v43
	v_mov_b32_e32 v43, v60
	v_lshl_add_u64 v[24:25], v[44:45], 0, v[162:163]
	v_mov_b32_e32 v44, v65
	v_mov_b32_e32 v45, v61
	v_pk_fma_f32 v[42:43], v[42:43], v[42:43], v[72:73]
	v_pk_add_f32 v[18:19], v[18:19], 1.0 op_sel_hi:[1,0]
	v_pk_fma_f32 v[72:73], v[44:45], v[44:45], v[42:43]
	v_and_b32_e32 v45, 0xffff0000, v46
	v_lshlrev_b32_e32 v44, 16, v46
	v_mov_b32_e32 v85, v45
	v_lshlrev_b32_e32 v42, 16, v47
	v_mov_b32_e32 v83, v44
	v_pk_mul_f32 v[84:85], v[84:85], v[84:85]
	v_and_b32_e32 v43, 0xffff0000, v47
	v_mov_b32_e32 v46, v52
	v_mov_b32_e32 v47, v42
	v_pk_fma_f32 v[82:83], v[82:83], v[82:83], v[84:85]
	v_mov_b32_e32 v81, v43
	v_pk_fma_f32 v[46:47], v[46:47], v[46:47], v[82:83]
	s_add_u32 s18, s18, s24
	v_pk_fma_f32 v[46:47], v[80:81], v[80:81], v[46:47]
	v_mov_b32_e32 v80, v68
	v_mov_b32_e32 v81, v62
	v_mov_b32_e32 v62, v69
	v_pk_add_f32 v[62:63], v[80:81], v[62:63]
	v_mov_b32_e32 v68, v46
	v_mov_b32_e32 v69, v72
	v_pk_add_f32 v[62:63], v[62:63], v[68:69]
	v_mov_b32_e32 v72, v47
	v_pk_add_f32 v[46:47], v[62:63], v[72:73]
	ds_bpermute_b32 v63, v11, v47
	ds_bpermute_b32 v62, v11, v46
	s_addc_u32 s19, s19, s25
	s_add_u32 s14, s14, s24
	s_addc_u32 s15, s15, s25
	s_waitcnt lgkmcnt(0)
	v_pk_add_f32 v[46:47], v[46:47], v[62:63]
	ds_bpermute_b32 v63, v74, v47
	ds_bpermute_b32 v62, v74, v46
	s_waitcnt lgkmcnt(0)
	v_pk_add_f32 v[46:47], v[46:47], v[62:63]
	ds_bpermute_b32 v63, v75, v47
	ds_bpermute_b32 v62, v75, v46
	s_waitcnt lgkmcnt(0)
	v_pk_add_f32 v[46:47], v[46:47], v[62:63]
	ds_bpermute_b32 v63, v76, v47
	ds_bpermute_b32 v62, v76, v46
	s_waitcnt lgkmcnt(0)
	v_pk_add_f32 v[46:47], v[46:47], v[62:63]
	ds_bpermute_b32 v63, v77, v47
	ds_bpermute_b32 v62, v77, v46
	s_waitcnt lgkmcnt(0)
	v_pk_add_f32 v[46:47], v[46:47], v[62:63]
	ds_bpermute_b32 v63, v78, v47
	ds_bpermute_b32 v62, v78, v46
	s_waitcnt lgkmcnt(0)
	v_pk_add_f32 v[46:47], v[46:47], v[62:63]
	s_nop 0
	v_pk_fma_f32 v[62:63], v[46:47], s[30:31], v[164:165] op_sel_hi:[1,0,0]
	s_nop 0
	v_mul_f32_e32 v11, 0x4b800000, v63
	v_cmp_gt_f32_e64 s[38:39], s50, v63
	v_cmp_gt_f32_e32 vcc, s50, v62
	s_nop 0
	v_cndmask_b32_e64 v11, v63, v11, s[38:39]
	v_rsq_f32_e32 v11, v11
	s_nop 0
	v_mul_f32_e32 v15, 0x45800000, v11
	v_cndmask_b32_e64 v68, v11, v15, s[38:39]
	v_mul_f32_e32 v11, 0x4b800000, v62
	v_cndmask_b32_e32 v11, v62, v11, vcc
	v_rsq_f32_e32 v11, v11
	v_pk_mul_f32 v[72:73], v[68:69], v[58:59] op_sel_hi:[0,1]
	v_pk_mul_f32 v[32:33], v[68:69], v[32:33] op_sel_hi:[0,1]
	s_waitcnt vmcnt(0)
	v_pk_mul_f32 v[32:33], v[6:7], v[32:33]
	v_mul_f32_e32 v15, 0x45800000, v11
	v_cndmask_b32_e32 v58, v11, v15, vcc
	v_pk_mul_f32 v[34:35], v[58:59], v[34:35] op_sel_hi:[0,1]
	v_pk_mul_f32 v[6:7], v[6:7], v[34:35]
	v_pk_fma_f32 v[32:33], v[32:33], v[20:21], v[2:3]
	v_pk_mul_f32 v[28:29], v[68:69], v[28:29] op_sel_hi:[0,1]
	v_pk_fma_f32 v[2:3], v[20:21], v[6:7], v[2:3]
	v_pk_mul_f32 v[6:7], v[58:59], v[26:27] op_sel_hi:[0,1]
	v_pk_mul_f32 v[28:29], v[8:9], v[28:29]
	v_pk_mul_f32 v[6:7], v[8:9], v[6:7]
	v_pk_fma_f32 v[28:29], v[28:29], v[18:19], v[4:5]
	v_pk_fma_f32 v[4:5], v[18:19], v[6:7], v[4:5]
	v_cvt_pk_bf16_f32 v32, v32, v33
	v_cvt_pk_bf16_f32 v33, v28, v29
	v_cvt_pk_bf16_f32 v2, v2, v3
	v_cvt_pk_bf16_f32 v3, v4, v5
	global_store_dwordx2 v[16:17], v[32:33], off sc1
	global_store_dwordx2 v[16:17], v[2:3], off offset:2048 sc1
	global_load_dwordx4 v[2:5], v14, s[6:7] offset:1024
	s_nop 0
	global_load_dwordx4 v[6:9], v[36:37], off
	global_load_dwordx4 v[18:21], v[30:31], off
	v_pk_mul_f32 v[74:75], v[68:69], v[56:57] op_sel_hi:[0,1]
	v_pk_mul_f32 v[26:27], v[58:59], v[50:51] op_sel_hi:[0,1]
	v_pk_mul_f32 v[34:35], v[58:59], v[48:49] op_sel_hi:[0,1]
	v_pk_mul_f32 v[56:57], v[68:69], v[66:67] op_sel_hi:[0,1]
	v_pk_mul_f32 v[46:47], v[68:69], v[64:65] op_sel_hi:[0,1]
	v_pk_mul_f32 v[48:49], v[58:59], v[54:55] op_sel_hi:[0,1]
	v_pk_mul_f32 v[50:51], v[58:59], v[52:53] op_sel_hi:[0,1]
	v_pk_mul_f32 v[32:33], v[68:69], v[70:71] op_sel_hi:[0,1]
	v_pk_mul_f32 v[28:29], v[68:69], v[60:61] op_sel_hi:[0,1]
	v_cmp_lt_i32_e32 vcc, s51, v10
	s_or_b64 s[12:13], vcc, s[12:13]
	s_waitcnt vmcnt(2)
	v_pk_mul_f32 v[30:31], v[72:73], v[2:3]
	v_pk_mul_f32 v[36:37], v[74:75], v[4:5]
	s_waitcnt vmcnt(0)
	v_pk_add_f32 v[18:19], v[18:19], 1.0 op_sel_hi:[1,0]
	v_pk_add_f32 v[20:21], v[20:21], 1.0 op_sel_hi:[1,0]
	v_pk_mul_f32 v[2:3], v[2:3], v[26:27]
	v_pk_mul_f32 v[4:5], v[4:5], v[34:35]
	v_pk_fma_f32 v[30:31], v[30:31], v[18:19], v[6:7]
	v_pk_fma_f32 v[36:37], v[36:37], v[20:21], v[8:9]
	v_pk_fma_f32 v[2:3], v[18:19], v[2:3], v[6:7]
	v_pk_fma_f32 v[4:5], v[20:21], v[4:5], v[8:9]
	v_cvt_pk_bf16_f32 v30, v30, v31
	v_cvt_pk_bf16_f32 v31, v36, v37
	v_cvt_pk_bf16_f32 v2, v2, v3
	v_cvt_pk_bf16_f32 v3, v4, v5
	global_store_dwordx2 v[16:17], v[30:31], off offset:512 sc1
	global_store_dwordx2 v[16:17], v[2:3], off offset:2560 sc1
	global_load_dwordx4 v[2:5], v14, s[6:7] offset:2048
	s_nop 0
	global_load_dwordx4 v[6:9], v[40:41], off
	global_load_dwordx4 v[18:21], v[38:39], off
	s_waitcnt vmcnt(2)
	v_pk_mul_f32 v[26:27], v[56:57], v[2:3]
	v_pk_mul_f32 v[30:31], v[46:47], v[4:5]
	s_waitcnt vmcnt(0)
	v_pk_add_f32 v[18:19], v[18:19], 1.0 op_sel_hi:[1,0]
	v_pk_add_f32 v[20:21], v[20:21], 1.0 op_sel_hi:[1,0]
	v_pk_mul_f32 v[2:3], v[48:49], v[2:3]
	v_pk_mul_f32 v[4:5], v[50:51], v[4:5]
	v_pk_fma_f32 v[26:27], v[26:27], v[18:19], v[6:7]
	v_pk_fma_f32 v[30:31], v[30:31], v[20:21], v[8:9]
	v_pk_fma_f32 v[2:3], v[2:3], v[18:19], v[6:7]
	v_pk_fma_f32 v[4:5], v[4:5], v[20:21], v[8:9]
	v_cvt_pk_bf16_f32 v26, v26, v27
	v_cvt_pk_bf16_f32 v27, v30, v31
	v_cvt_pk_bf16_f32 v2, v2, v3
	v_cvt_pk_bf16_f32 v3, v4, v5
	global_store_dwordx2 v[16:17], v[26:27], off offset:1024 sc1
	global_store_dwordx2 v[16:17], v[2:3], off offset:3072 sc1
	global_load_dwordx4 v[2:5], v14, s[6:7] offset:3072
	s_nop 0
	global_load_dwordx4 v[6:9], v[24:25], off
	global_load_dwordx4 v[18:21], v[22:23], off
	s_waitcnt vmcnt(2)
	v_pk_mul_f32 v[14:15], v[32:33], v[2:3]
	v_pk_mul_f32 v[22:23], v[28:29], v[4:5]
	s_waitcnt vmcnt(0)
	v_pk_add_f32 v[18:19], v[18:19], 1.0 op_sel_hi:[1,0]
	v_pk_add_f32 v[20:21], v[20:21], 1.0 op_sel_hi:[1,0]
	v_pk_fma_f32 v[14:15], v[14:15], v[18:19], v[6:7]
	v_pk_fma_f32 v[22:23], v[22:23], v[20:21], v[8:9]
	v_cvt_pk_bf16_f32 v14, v14, v15
	v_cvt_pk_bf16_f32 v15, v22, v23
	global_store_dwordx2 v[16:17], v[14:15], off offset:1536 sc1
	v_pk_mul_f32 v[14:15], v[58:59], v[44:45] op_sel_hi:[0,1]
	v_pk_mul_f32 v[2:3], v[14:15], v[2:3]
	s_nop 0
	v_pk_fma_f32 v[2:3], v[2:3], v[18:19], v[6:7]
	v_pk_mul_f32 v[6:7], v[58:59], v[42:43] op_sel_hi:[0,1]
	v_pk_mul_f32 v[4:5], v[6:7], v[4:5]
	v_cvt_pk_bf16_f32 v2, v2, v3
	v_pk_fma_f32 v[4:5], v[4:5], v[20:21], v[8:9]
	s_nop 0
	v_cvt_pk_bf16_f32 v3, v4, v5
	global_store_dwordx2 v[16:17], v[2:3], off offset:3584 sc1
	s_andn2_b64 exec, exec, s[12:13]
	s_cbranch_execnz .LBB0_205
.LBB0_206:
	s_or_b64 exec, exec, s[2:3]
	s_waitcnt vmcnt(0)
	s_barrier
	v_lshrrev_b32_e32 v2, 6, v1
	s_nop 1
	v_readfirstlane_b32 s0, v2
	s_cmp_lg_u32 s0, 0
	s_cbranch_scc1 .Lpf_rel2
	v_readlane_b32 s12, v253, 5
	v_readlane_b32 s13, v253, 6
	v_readlane_b32 s0, v253, 0
	s_lshr_b32 s0, s0, 4
	s_lshl_b32 s0, s0, 2
	s_add_u32 s0, s0, 0x80
	v_lshlrev_b32_e32 v2, 6, v194
	v_add_u32_e32 v2, s0, v2
	v_mov_b32_e32 v3, 1
	s_nop 3
	s_mov_b64 exec, 3
	global_atomic_add v2, v3, s[12:13]
	s_mov_b64 exec, -1
.Lpf_rel2:
	s_mov_b64 s[2:3], 0
.LBB0_207:
	s_andn2_b64 vcc, exec, s[2:3]
	s_cbranch_vccnz .LBB0_313
	s_waitcnt vmcnt(0) lgkmcnt(0)
	v_readlane_b32 s2, v253, 0
	v_readlane_b32 s3, v254, 4
	v_readlane_b32 s30, v252, 0
	v_readlane_b32 s31, v252, 1
	v_readlane_b32 s24, v252, 2
	v_readlane_b32 s25, v252, 3
	v_readlane_b32 s82, v252, 8
	v_readlane_b32 s80, v254, 52
	v_readlane_b32 s81, v254, 53
	s_mov_b32 s18, s10
	s_mov_b32 s19, s11
	s_and_b32 s77, s2, 7
	s_lshl_b32 s77, s77, 2
	s_lshr_b32 s78, s2, 3
	s_lshr_b32 s79, s3, 3
	s_cmp_gt_u32 s78, 31
	s_cbranch_scc1 .LBB0_312
	v_and_b32_e32 v170, 15, v1
	v_bfe_u32 v171, v1, 4, 2
	v_bfe_u32 v172, v1, 6, 1
	v_lshrrev_b32_e32 v173, 7, v1
	v_and_b32_e32 v162, 7, v170
	v_xor_b32_e32 v162, v162, v171
	v_lshlrev_b32_e32 v162, 4, v162
	v_lshlrev_b32_e32 v200, 13, v173
	v_lshl_add_u32 v200, v170, 7, v200
	v_add_u32_e32 v200, v200, v162
	v_xor_b32_e32 v201, 64, v200
	v_lshlrev_b32_e32 v202, 13, v172
	v_lshl_add_u32 v202, v170, 7, v202
	v_add_u32_e32 v202, v202, v162
	v_add_u32_e32 v202, 0x8000, v202
	v_xor_b32_e32 v203, 64, v202
	v_lshl_add_u32 v162, v173, 6, v170
	v_lshlrev_b32_e32 v172, 6, v172
	v_lshl_add_u32 v172, v171, 2, v172
	v_lshlrev_b32_e32 v190, 2, v172
	v_lshlrev_b32_e32 v206, 11, v162
	v_lshl_add_u32 v206, v172, 1, v206
	v_add_u32_e32 v207, 0x8000, v206
	v_add_u32_e32 v208, 0x10000, v206
	v_add_u32_e32 v209, 0x18000, v206
	v_lshlrev_b32_e32 v210, 12, v162
	v_add_u32_e32 v210, v210, v190
	v_add_u32_e32 v211, 0x10000, v210
	v_add_u32_e32 v168, 0x20000, v210
	v_add_u32_e32 v169, 0x30000, v210
	v_lshrrev_b32_e32 v170, 3, v1
	v_and_b32_e32 v171, 7, v1
	v_and_b32_e32 v173, 7, v170
	v_xor_b32_e32 v171, v171, v173
	v_lshlrev_b32_e32 v171, 4, v171
	v_mul_u32_u24_e32 v196, 0x800, v170
	v_add_u32_e32 v196, v196, v171
	v_add_u32_e32 v197, 0x20000, v196
	v_add_u32_e32 v198, 0x40000, v196
	v_add_u32_e32 v199, 0x60000, v196
	v_lshrrev_b32_e32 v170, 6, v1
	v_lshlrev_b32_e32 v170, 10, v170
	s_nop 0
	v_readfirstlane_b32 s76, v170

.LBB0_727:
	s_mov_b64 s[2:3], s[46:47]
	s_add_i32 s18, s2, 1
	s_cmp_ge_i32 s18, s3
	v_readlane_b32 s30, v254, 6
	v_readlane_b32 s38, v254, 8
	v_readlane_b32 s56, v254, 22
	v_readlane_b32 s31, v254, 7
	v_readlane_b32 s39, v254, 9
	v_readlane_b32 s57, v254, 23
	s_cbranch_scc1 .LBB0_781
	s_cmp_eq_u32 s2, 5
	s_cbranch_scc1 .LBB0_781
	s_cmp_eq_u32 s2, 14
	s_cbranch_scc1 .LBB0_781
	s_cmp_eq_u32 s2, 9
	s_cbranch_scc1 .LBB0_781
	s_cmp_eq_u32 s2, 18
	s_cbranch_scc1 .LBB0_781
	s_cmp_eq_u32 s2, 4
	s_cbranch_scc1 .LBB0_781
	s_cmp_eq_u32 s2, 13
	s_cbranch_scc1 .LBB0_781
	s_cmp_eq_u32 s2, 0
	s_cbranch_scc1 .LBB0_781
	s_cmp_eq_u32 s2, 6
	s_cbranch_scc1 .LBB0_781
	s_cmp_eq_u32 s2, 15
	s_cbranch_scc1 .LBB0_781
	s_waitcnt vmcnt(0)
	s_waitcnt lgkmcnt(0)
	s_barrier
	s_mov_b64 s[2:3], exec
	v_readlane_b32 s4, v253, 7
	v_readlane_b32 s5, v253, 8
	s_and_b64 s[4:5], s[2:3], s[4:5]
	s_mov_b64 exec, s[4:5]
	s_cbranch_execz .LBB0_780
	s_add_i32 s13, 0, 0x24000
	s_mov_b64 s[4:5], src_shared_base
	s_cmp_lg_u32 s13, -1
	s_cselect_b32 s4, s13, 0
	s_cselect_b32 s6, s5, 0
	s_add_i32 s12, 0, 0x24004
	s_cmp_lg_u32 s12, -1
	v_mov_b32_e32 v2, s4
	v_mov_b32_e32 v3, s6
	s_cselect_b32 s4, s12, 0
	s_cselect_b32 s5, s5, 0
	s_waitcnt vmcnt(0) expcnt(0) lgkmcnt(0)
	s_and_b32 s4, s101, 0xffff
	v_mov_b32_e32 v4, s4
	v_mov_b32_e32 v2, s4
	v_mov_b32_e32 v3, s5
	s_lshr_b32 s4, s101, 16
	v_mov_b32_e32 v2, s4
	s_waitcnt vmcnt(0) lgkmcnt(0)
	v_cmp_eq_u32_e32 vcc, 0, v4
	s_and_saveexec_b64 s[4:5], vcc
	s_cbranch_execz .LBB0_744
	s_mov_b32 s14, 1
	s_branch .LBB0_732
